# stack3 + gate projection rows moved to the 64 workgroups with 13 GEMM rounds
# baseline (speedup 1.0000x reference)
; #define LAS __attribute__((address_space(3)))
; DI void phase_gates(const Params& P, int l, int bid, int nb, LAS unsigned char* lds) {
;     const int wid = threadIdx.x >> 6, lane = threadIdx.x & 63, r = lane & 31, h = lane >> 5;
;     const bf16_t* XB = (const bf16_t*)(P.ws + WS_XB); const bf16_t* Wg = (const bf16_t*)(P.ws + WS_WIN) + ((size_t)l * NIN + NMAIN) * DM;
;     float* LR = (float*)(P.ws + WS_LR);
;     __syncthreads();
.LBB0_184:
	s_cmp_lt_i32 s72, 2
	s_cselect_b64 s[0:1], -1, 0
	s_cmp_gt_i32 s73, 1
	s_cselect_b64 s[2:3], -1, 0
	s_and_b64 s[0:1], s[0:1], s[2:3]
	s_andn2_b64 vcc, exec, s[0:1]
	v_lshlrev_b32_e32 v204, 4, v0
	v_bfe_u32 v203, v0, 8, 2
	s_cbranch_vccnz .LBB0_332
	v_and_b32_e32 v131, 0x3ff, v0
	v_or_b32_e32 v2, 0x600, v131
	v_and_b32_e32 v13, 0xff0, v204
	v_lshrrev_b32_e32 v10, 8, v2
	v_or_b32_e32 v4, 0x200, v131
	v_lshl_or_b32 v6, v10, 12, v13
	v_mov_b32_e32 v7, 0
	v_lshrrev_b32_e32 v11, 8, v4
	v_lshl_add_u64 v[2:3], s[50:51], 0, v[6:7]
	v_lshl_or_b32 v6, v11, 12, v13
	v_bfe_u32 v12, v0, 8, 2
	s_mov_b64 s[0:1], 0x1600000
	v_lshl_add_u64 v[4:5], s[50:51], 0, v[6:7]
	v_lshl_or_b32 v6, v12, 12, v13
	v_add_u32_e32 v9, 0, v13
	s_movk_i32 s2, 0x1010
	v_mul_u32_u24_e32 v8, 0x1010, v1
	v_lshl_add_u64 v[2:3], v[2:3], 0, s[0:1]
	v_lshl_add_u64 v[4:5], v[4:5], 0, s[0:1]
	v_lshl_add_u64 v[6:7], s[50:51], 0, v[6:7]
	s_mov_b64 s[0:1], 0
	s_waitcnt lgkmcnt(0)
	s_cmp_lt_u32 s33, 0xc0
	s_cbranch_scc1 .Lgates_skip_0
	s_barrier

; #define LAS __attribute__((address_space(3)))
; DI void phase_gates(const Params& P, int l, int bid, int nb, LAS unsigned char* lds) {
;     ...
;     __syncthreads();
; #pragma unroll 4
;     for (int q = 0; q < 16; ++q) { const int e = q * 512 + threadIdx.x, n = e >> 8, c16 = e & 255;
;         *(LAS u32x4*)(lds + n * 4112 + c16 * 16) = *(const u32x4*)(Wg + (size_t)n * DM + c16 * 8); }
;     __syncthreads();
;     const LAS unsigned char* bp = lds + r * 4112 + 64 * h;
;     for (int t = bid * 8 + wid; t < MTOK / 32; t += nb * 8) {
;         const bf16_t* ap = XB + (size_t)(t * 32 + r) * DM + 32 * h;
.Lgates_skip_0:
	s_sub_i32 s95, s33, 0xc0
	s_cmp_lt_i32 s95, 0
	s_cselect_b32 s95, 0x1000, s95
	v_lshrrev_b32_e32 v2, 6, v131
	v_lshl_add_u32 v95, s95, 3, v2
	s_add_u32 s4, s50, 0x1f940000
	s_movk_i32 s0, 0x500
	v_lshrrev_b32_e32 v94, 5, v131
	s_addc_u32 s5, s51, 0
	v_cmp_gt_i32_e32 vcc, s0, v95
	s_waitcnt lgkmcnt(0)
	s_barrier
	s_and_saveexec_b64 s[0:1], vcc
	s_cbranch_execz .LBB0_194
	v_and_b32_e32 v3, 1, v94
	v_lshlrev_b32_e32 v82, 6, v3
	v_mov_b32_e32 v83, 0
	v_add3_u32 v96, 0, v8, v82
	v_lshlrev_b32_e32 v97, 2, v3
	v_lshl_add_u64 v[84:85], s[4:5], 0, v[82:83]
	v_lshlrev_b32_e32 v82, 2, v1
	v_lshlrev_b32_e32 v3, 1, v131
	v_lshl_add_u64 v[4:5], s[50:51], 0, v[82:83]
	s_mov_b64 s[2:3], 0x1f440000
	v_and_b32_e32 v82, 64, v3
	v_lshlrev_b32_e32 v2, 5, v2
	v_lshl_add_u64 v[86:87], v[4:5], 0, s[2:3]
	v_lshl_add_u64 v[4:5], s[50:51], 0, v[82:83]
	s_mov_b64 s[2:3], 0x1f940100
	v_lshl_add_u32 v2, s95, 8, v2
	s_movk_i32 s10, 0x200
	v_lshl_add_u64 v[88:89], v[4:5], 0, s[2:3]
	v_or_b32_e32 v90, v2, v1
	s_movk_i32 s11, 0x4000
	s_mov_b64 s[2:3], 0
	s_mov_b64 s[6:7], 0x100
	s_movk_i32 s12, 0x4ff
	s_branch .LBB0_190

; #define LAS __attribute__((address_space(3)))
; DI void phase_gates(const Params& P, int l, int bid, int nb, LAS unsigned char* lds) {
;     const int wid = threadIdx.x >> 6, lane = threadIdx.x & 63, r = lane & 31, h = lane >> 5;
;     const bf16_t* XB = (const bf16_t*)(P.ws + WS_XB); const bf16_t* Wg = (const bf16_t*)(P.ws + WS_WIN) + ((size_t)l * NIN + NMAIN) * DM;
;     float* LR = (float*)(P.ws + WS_LR);
;     __syncthreads();
.LBB0_746:
	s_cmp_lt_i32 s72, 8
	s_cselect_b64 s[0:1], -1, 0
	s_cmp_gt_i32 s73, 7
	s_cselect_b64 s[2:3], -1, 0
	s_and_b64 s[0:1], s[0:1], s[2:3]
	s_andn2_b64 vcc, exec, s[0:1]
	s_cbranch_vccnz .LBB0_894
	v_and_b32_e32 v131, 0x3ff, v0
	v_or_b32_e32 v2, 0x600, v131
	v_and_b32_e32 v12, 0xff0, v204
	v_lshrrev_b32_e32 v10, 8, v2
	v_or_b32_e32 v4, 0x200, v131
	v_lshl_or_b32 v6, v10, 12, v12
	s_waitcnt lgkmcnt(0)
	v_mov_b32_e32 v7, 0
	v_lshrrev_b32_e32 v11, 8, v4
	v_lshl_add_u64 v[2:3], s[50:51], 0, v[6:7]
	v_lshl_or_b32 v6, v11, 12, v12
	s_mov_b64 s[0:1], 0x2c20000
	v_lshl_add_u64 v[4:5], s[50:51], 0, v[6:7]
	v_lshl_or_b32 v6, v203, 12, v12
	v_add_u32_e32 v9, 0, v12
	s_movk_i32 s2, 0x1010
	v_mul_u32_u24_e32 v8, 0x1010, v1
	v_lshl_add_u64 v[2:3], v[2:3], 0, s[0:1]
	v_lshl_add_u64 v[4:5], v[4:5], 0, s[0:1]
	v_lshl_add_u64 v[6:7], s[50:51], 0, v[6:7]
	s_mov_b64 s[0:1], 0
	s_waitcnt vmcnt(0)
	s_cmp_lt_u32 s33, 0xc0
	s_cbranch_scc1 .Lgates_skip_1
	s_barrier
